# up-proj sample-tile epilogue: all eight conv-state row addresses requested once at its start (cache warm-up) so the per-group loads no longer pay full memory latency
# baseline (speedup 1.0000x reference)
.LBB0_1402:
	s_lshl_b32 s23, s73, 6
	v_or_b32_e32 v162, s23, v169
	v_mov_b32_e32 v160, v167
	v_lshl_add_u32 v128, v162, 3, s67
	ds_read_b64 v[128:129], v128
	s_lshl_b32 s22, s56, 8
	s_add_i32 s23, s23, s22
	v_mov_b32_e32 v226, v174
	v_ashrrev_i32_e32 v227, 31, v174
	s_add_i32 s4, s23, 0xffff0000
	s_ashr_i32 s4, s4, 4
	s_mul_i32 s8, s4, 0x5800
	s_mul_hi_i32 s5, s4, 0x5800
	s_add_u32 s8, s51, s8
	s_addc_u32 s9, s83, s5
	v_lshl_add_u64 v[222:223], v[226:227], 2, s[8:9]
	v_lshl_add_u64 v[224:225], v[222:223], 0, s[34:35]
	global_load_dwordx4 v[228:231], v[222:223], off
	global_load_dwordx4 v[228:231], v[224:225], off
	s_add_i32 s4, s23, 0xffff0010
	s_ashr_i32 s4, s4, 4
	s_mul_i32 s8, s4, 0x5800
	s_mul_hi_i32 s5, s4, 0x5800
	s_add_u32 s8, s51, s8
	s_addc_u32 s9, s83, s5
	v_lshl_add_u64 v[222:223], v[226:227], 2, s[8:9]
	v_lshl_add_u64 v[224:225], v[222:223], 0, s[34:35]
	global_load_dwordx4 v[228:231], v[222:223], off
	global_load_dwordx4 v[228:231], v[224:225], off
	s_add_i32 s4, s23, 0xffff0020
	s_ashr_i32 s4, s4, 4
	s_mul_i32 s8, s4, 0x5800
	s_mul_hi_i32 s5, s4, 0x5800
	s_add_u32 s8, s51, s8
	s_addc_u32 s9, s83, s5
	v_lshl_add_u64 v[222:223], v[226:227], 2, s[8:9]
	v_lshl_add_u64 v[224:225], v[222:223], 0, s[34:35]
	global_load_dwordx4 v[228:231], v[222:223], off
	global_load_dwordx4 v[228:231], v[224:225], off
	s_add_i32 s4, s23, 0xffff0030
	s_ashr_i32 s4, s4, 4
	s_mul_i32 s8, s4, 0x5800
	s_mul_hi_i32 s5, s4, 0x5800
	s_add_u32 s8, s51, s8
	s_addc_u32 s9, s83, s5
	v_lshl_add_u64 v[222:223], v[226:227], 2, s[8:9]
	v_lshl_add_u64 v[224:225], v[222:223], 0, s[34:35]
	global_load_dwordx4 v[228:231], v[222:223], off
	global_load_dwordx4 v[228:231], v[224:225], off
	s_add_i32 s4, s23, 0xffff0080
	s_ashr_i32 s4, s4, 4
	s_mul_i32 s8, s4, 0x5800
	s_mul_hi_i32 s5, s4, 0x5800
	s_add_u32 s8, s51, s8
	s_addc_u32 s9, s83, s5
	v_lshl_add_u64 v[222:223], v[226:227], 2, s[8:9]
	v_lshl_add_u64 v[224:225], v[222:223], 0, s[34:35]
	global_load_dwordx4 v[228:231], v[222:223], off
	global_load_dwordx4 v[228:231], v[224:225], off
	s_add_i32 s4, s23, 0xffff0090
	s_ashr_i32 s4, s4, 4
	s_mul_i32 s8, s4, 0x5800
	s_mul_hi_i32 s5, s4, 0x5800
	s_add_u32 s8, s51, s8
	s_addc_u32 s9, s83, s5
	v_lshl_add_u64 v[222:223], v[226:227], 2, s[8:9]
	v_lshl_add_u64 v[224:225], v[222:223], 0, s[34:35]
	global_load_dwordx4 v[228:231], v[222:223], off
	global_load_dwordx4 v[228:231], v[224:225], off
	s_add_i32 s4, s23, 0xffff00a0
	s_ashr_i32 s4, s4, 4
	s_mul_i32 s8, s4, 0x5800
	s_mul_hi_i32 s5, s4, 0x5800
	s_add_u32 s8, s51, s8
	s_addc_u32 s9, s83, s5
	v_lshl_add_u64 v[222:223], v[226:227], 2, s[8:9]
	v_lshl_add_u64 v[224:225], v[222:223], 0, s[34:35]
	global_load_dwordx4 v[228:231], v[222:223], off
	global_load_dwordx4 v[228:231], v[224:225], off
	s_add_i32 s4, s23, 0xffff00b0
	s_ashr_i32 s4, s4, 4
	s_mul_i32 s8, s4, 0x5800
	s_mul_hi_i32 s5, s4, 0x5800
	s_add_u32 s8, s51, s8
	s_addc_u32 s9, s83, s5
	v_lshl_add_u64 v[222:223], v[226:227], 2, s[8:9]
	v_lshl_add_u64 v[224:225], v[222:223], 0, s[34:35]
	global_load_dwordx4 v[228:231], v[222:223], off
	global_load_dwordx4 v[228:231], v[224:225], off
	s_add_i32 s4, s23, 0xffff0000
	s_ashr_i32 s4, s4, 4
	s_waitcnt lgkmcnt(0)
	v_pk_mul_f32 v[144:145], v[128:129], s[96:97] op_sel_hi:[1,0]
	s_mul_i32 s8, s4, 0x5800
	v_fma_f32 v128, -v144, v144, v145
	v_max_f32_e32 v128, 0, v128
	v_add_f32_e32 v128, 0x3727c5ac, v128
	v_rsq_f32_e32 v152, v128
	ds_read_b128 v[128:131], v160 offset:2048
	ds_read_b128 v[132:135], v160 offset:2064
	ds_read_b128 v[136:139], v160 offset:2560
	ds_read_b128 v[140:143], v160 offset:2576
	s_mul_hi_i32 s5, s4, 0x5800
	s_add_u32 s8, s51, s8
	v_mul_f32_e64 v154, v152, -v144
	s_waitcnt lgkmcnt(0)
	v_pk_fma_f32 v[128:129], v[128:129], v[154:155], v[136:137] op_sel_hi:[1,0,1]
	v_pk_fma_f32 v[130:131], v[130:131], v[154:155], v[138:139] op_sel_hi:[1,0,1]
	v_pk_fma_f32 v[132:133], v[132:133], v[154:155], v[140:141] op_sel_hi:[1,0,1]
	v_pk_fma_f32 v[134:135], v[134:135], v[154:155], v[142:143] op_sel_hi:[1,0,1]
	ds_read_b128 v[136:139], v160 offset:3072
	ds_read_b128 v[144:147], v160 offset:3088
	ds_read_b128 v[140:143], v160 offset:3584
	ds_read_b128 v[148:151], v160 offset:3600
	v_ashrrev_i32_e32 v175, 31, v174
	s_addc_u32 s9, s83, s5
	v_pk_fma_f32 v[128:129], v[124:125], v[152:153], v[128:129] op_sel_hi:[1,0,1]
	s_waitcnt lgkmcnt(0)
	v_pk_fma_f32 v[140:141], v[136:137], v[154:155], v[140:141] op_sel_hi:[1,0,1]
	v_pk_fma_f32 v[136:137], v[138:139], v[154:155], v[142:143] op_sel_hi:[1,0,1]
	v_pk_fma_f32 v[138:139], v[146:147], v[154:155], v[150:151] op_sel_hi:[1,0,1]
	v_pk_fma_f32 v[142:143], v[94:95], v[152:153], v[136:137] op_sel_hi:[1,0,1]
	v_pk_fma_f32 v[136:137], v[144:145], v[154:155], v[148:149] op_sel_hi:[1,0,1]
	v_pk_fma_f32 v[130:131], v[126:127], v[152:153], v[130:131] op_sel_hi:[1,0,1]
	v_pk_fma_f32 v[132:133], v[120:121], v[152:153], v[132:133] op_sel_hi:[1,0,1]
	v_pk_fma_f32 v[134:135], v[122:123], v[152:153], v[134:135] op_sel_hi:[1,0,1]
	v_pk_fma_f32 v[136:137], v[88:89], v[152:153], v[136:137] op_sel_hi:[1,0,1]
	v_pk_fma_f32 v[138:139], v[90:91], v[152:153], v[138:139] op_sel_hi:[1,0,1]
	v_pk_fma_f32 v[140:141], v[92:93], v[152:153], v[140:141] op_sel_hi:[1,0,1]
	v_lshl_add_u64 v[152:153], v[174:175], 2, s[8:9]
	global_load_dwordx4 v[144:147], v[152:153], off offset:16
	global_load_dwordx4 v[148:151], v[152:153], off
	v_lshl_add_u64 v[156:157], v[152:153], 0, s[34:35]
	v_add_co_u32_e64 v152, s[48:49], s33, v152
	v_cmp_eq_u32_e64 s[42:43], 1, v169
	s_nop 0
	v_addc_co_u32_e64 v153, s[48:49], 0, v153, s[48:49]
	global_load_dwordx4 v[152:155], v[152:153], off offset:3072
	s_nop 0
	global_load_dwordx4 v[156:159], v[156:157], off offset:16
	v_cmp_lt_u32_e32 vcc, 1, v169
	v_mov_b32_dpp v179, v128 row_ror:2 row_mask:0xf bank_mask:0xf
	v_mov_b32_dpp v185, v129 row_ror:2 row_mask:0xf bank_mask:0xf
	v_mov_b32_dpp v164, v132 row_ror:2 row_mask:0xf bank_mask:0xf
	v_mov_b32_dpp v177, v133 row_ror:2 row_mask:0xf bank_mask:0xf
	v_cmp_eq_u32_e64 s[44:45], 0, v169
	v_mov_b32_dpp v187, v128 row_ror:1 row_mask:0xf bank_mask:0xf
	v_mov_b32_dpp v188, v129 row_ror:1 row_mask:0xf bank_mask:0xf
	v_mov_b32_dpp v180, v130 row_ror:1 row_mask:0xf bank_mask:0xf
	v_mov_b32_dpp v186, v131 row_ror:1 row_mask:0xf bank_mask:0xf
	v_mov_b32_dpp v173, v130 row_ror:2 row_mask:0xf bank_mask:0xf
	v_mov_b32_dpp v181, v131 row_ror:2 row_mask:0xf bank_mask:0xf
	v_mov_b32_dpp v176, v132 row_ror:1 row_mask:0xf bank_mask:0xf
	v_mov_b32_dpp v184, v133 row_ror:1 row_mask:0xf bank_mask:0xf
	v_mov_b32_dpp v165, v134 row_ror:1 row_mask:0xf bank_mask:0xf
	v_mov_b32_dpp v178, v135 row_ror:1 row_mask:0xf bank_mask:0xf
	v_mov_b32_dpp v163, v134 row_ror:2 row_mask:0xf bank_mask:0xf
	v_mov_b32_dpp v171, v135 row_ror:2 row_mask:0xf bank_mask:0xf
	s_movk_i32 s5, 0x1600
	s_cmp_eq_u32 s73, 0
	v_cmp_gt_u32_e64 s[46:47], 2, v169
	s_waitcnt vmcnt(0)
	v_cndmask_b32_e64 v148, v148, v152, s[42:43]
	v_cndmask_b32_e64 v149, v149, v153, s[42:43]
	v_cndmask_b32_e64 v144, v144, v156, s[42:43]
	v_cndmask_b32_e64 v145, v145, v157, s[42:43]
	v_cndmask_b32_e32 v191, v149, v185, vcc
	v_cndmask_b32_e32 v190, v148, v179, vcc
	v_cndmask_b32_e64 v148, v150, v154, s[42:43]
	v_cndmask_b32_e64 v149, v151, v155, s[42:43]
	v_cndmask_b32_e32 v207, v145, v177, vcc
	v_cndmask_b32_e32 v206, v144, v164, vcc
	v_cndmask_b32_e64 v144, v146, v158, s[42:43]
	v_cndmask_b32_e64 v145, v147, v159, s[42:43]
	v_cndmask_b32_e64 v189, v188, v153, s[44:45]
	v_cndmask_b32_e64 v188, v187, v152, s[44:45]
	v_cndmask_b32_e64 v203, v186, v155, s[44:45]
	v_cndmask_b32_e64 v202, v180, v154, s[44:45]
	v_cndmask_b32_e32 v181, v149, v181, vcc
	v_cndmask_b32_e32 v180, v148, v173, vcc
	v_cndmask_b32_e64 v205, v184, v157, s[44:45]
	v_cndmask_b32_e64 v204, v176, v156, s[44:45]
	v_cndmask_b32_e64 v209, v178, v159, s[44:45]
	v_cndmask_b32_e64 v208, v165, v158, s[44:45]
	v_cndmask_b32_e32 v165, v145, v171, vcc
	v_cndmask_b32_e32 v164, v144, v163, vcc
	ds_read_b128 v[144:147], v160
	ds_read_b128 v[148:151], v160 offset:16
	ds_read_b128 v[152:155], v160 offset:512
	ds_read_b128 v[156:159], v160 offset:528
	ds_read_b128 v[176:179], v160 offset:1024
	ds_read_b128 v[184:187], v160 offset:1040
	ds_read_b128 v[194:197], v160 offset:1536
	ds_read_b128 v[198:201], v160 offset:1552
	s_waitcnt lgkmcnt(1)
	v_pk_fma_f32 v[144:145], v[144:145], v[190:191], v[194:195]
	s_nop 0
	v_pk_fma_f32 v[144:145], v[188:189], v[152:153], v[144:145]
	v_pk_fma_f32 v[146:147], v[146:147], v[180:181], v[196:197]
	v_pk_fma_f32 v[144:145], v[128:129], v[176:177], v[144:145]
	v_pk_fma_f32 v[146:147], v[202:203], v[154:155], v[146:147]
	v_pk_mul_f32 v[152:153], v[144:145], s[20:21] op_sel_hi:[1,0]
	v_pk_mul_f32 v[144:145], v[140:141], v[144:145]
	v_exp_f32_e32 v152, v152
	v_exp_f32_e32 v153, v153
	v_pk_fma_f32 v[146:147], v[130:131], v[178:179], v[146:147]
	s_waitcnt lgkmcnt(0)
	v_pk_fma_f32 v[148:149], v[148:149], v[206:207], v[198:199]
	v_pk_fma_f32 v[150:151], v[150:151], v[164:165], v[200:201]
	v_pk_add_f32 v[152:153], v[152:153], 1.0 op_sel_hi:[1,0]
	v_pk_fma_f32 v[148:149], v[204:205], v[156:157], v[148:149]
	v_rcp_f32_e32 v152, v152
	v_rcp_f32_e32 v153, v153
	v_pk_fma_f32 v[148:149], v[132:133], v[184:185], v[148:149]
	v_pk_fma_f32 v[150:151], v[208:209], v[158:159], v[150:151]
	v_pk_mul_f32 v[144:145], v[144:145], v[152:153]
	v_pk_mul_f32 v[152:153], v[146:147], s[20:21] op_sel_hi:[1,0]
	v_pk_mul_f32 v[146:147], v[142:143], v[146:147]
	v_exp_f32_e32 v152, v152
	v_exp_f32_e32 v153, v153
	v_pk_fma_f32 v[150:151], v[134:135], v[186:187], v[150:151]
	v_cvt_pk_bf16_f32 v144, v144, v145
	v_pk_add_f32 v[152:153], v[152:153], 1.0 op_sel_hi:[1,0]
	s_nop 0
	v_rcp_f32_e32 v152, v152
	v_rcp_f32_e32 v153, v153
	s_nop 0
	v_pk_mul_f32 v[146:147], v[146:147], v[152:153]
	v_pk_mul_f32 v[152:153], v[148:149], s[20:21] op_sel_hi:[1,0]
	v_pk_mul_f32 v[148:149], v[136:137], v[148:149]
	v_exp_f32_e32 v152, v152
	v_exp_f32_e32 v153, v153
	v_cvt_pk_bf16_f32 v145, v146, v147
	v_pk_add_f32 v[152:153], v[152:153], 1.0 op_sel_hi:[1,0]
	s_nop 0
	v_rcp_f32_e32 v152, v152
	v_rcp_f32_e32 v153, v153
	s_nop 0
	v_pk_mul_f32 v[148:149], v[148:149], v[152:153]
	v_pk_mul_f32 v[152:153], v[150:151], s[20:21] op_sel_hi:[1,0]
	v_pk_mul_f32 v[150:151], v[138:139], v[150:151]
	v_exp_f32_e32 v152, v152
	v_exp_f32_e32 v153, v153
	v_cvt_pk_bf16_f32 v146, v148, v149
	v_mov_b64_e32 v[148:149], s[60:61]
	v_pk_add_f32 v[152:153], v[152:153], 1.0 op_sel_hi:[1,0]
	s_nop 0
	v_rcp_f32_e32 v152, v152
	v_rcp_f32_e32 v153, v153
	s_nop 0
	v_pk_mul_f32 v[150:151], v[150:151], v[152:153]
	s_nop 0
	v_cvt_pk_bf16_f32 v147, v150, v151
	v_add_u32_e32 v150, s22, v162
	v_mad_i64_i32 v[148:149], s[8:9], v150, s5, v[148:149]
	s_cselect_b64 s[8:9], -1, 0
	v_lshl_add_u64 v[148:149], v[174:175], 1, v[148:149]
	s_and_b64 s[18:19], s[8:9], s[46:47]
	global_store_dwordx4 v[148:149], v[144:147], off
	s_and_saveexec_b64 s[8:9], s[18:19]
	s_cbranch_execz .LBB0_1404
	v_readlane_b32 s18, v255, 6
	v_readlane_b32 s19, v255, 7
	v_lshl_or_b32 v150, s56, 1, v169
	s_movk_i32 s5, 0x2c00
	v_mov_b64_e32 v[144:145], s[18:19]
	v_mad_u64_u32 v[144:145], s[18:19], v150, s5, v[144:145]
	v_readlane_b32 s18, v255, 8
	v_readlane_b32 s19, v255, 9
	v_lshlrev_b64 v[146:147], 2, v[174:175]
	v_lshl_add_u64 v[144:145], v[144:145], 0, v[146:147]
	v_mov_b64_e32 v[148:149], s[18:19]
	v_mad_u64_u32 v[148:149], s[18:19], v150, s5, v[148:149]
	v_lshl_add_u64 v[146:147], v[148:149], 0, v[146:147]
	global_store_dwordx4 v[144:145], v[128:131], off
	global_store_dwordx4 v[144:145], v[132:135], off offset:16
	global_store_dwordx4 v[146:147], v[140:143], off
	global_store_dwordx4 v[146:147], v[136:139], off offset:16
